# code placement: 64-byte alignment of the A and C attention loop heads (on top of A DMA restructure)
# baseline (speedup 1.0000x reference)
; template <int TYPE, bool FIXREF>
; DI void attn_dense_unit(const Params& p, int layer, int head, int qb, char* lds, float bref) {
;     ...
;   } else {
;     const bf16_t* qp = Z + (size_t)q * ZP + ZC_QC + head * 64 + 8 * h;
;     float x[4][8]; float ss = 0.f;
; #pragma unroll
;     for (int d0 = 0; d0 < 4; ++d0) { unpack8(*(const u32x4*)(qp + d0 * 16), x[d0]);
; #pragma unroll
;       for (int j = 0; j < 8; ++j) ss += x[d0][j] * x[d0][j]; }
;     ss += __shfl_xor(ss, 32);
;     const float rs = rsqrtf(ss * (1.0f / 64.0f) + 1e-6f);
;     const float* gq = p.c_q_norm + layer * 64;
; #pragma unroll
;     for (int d0 = 0; d0 < 4; ++d0)
; #pragma unroll
;       for (int j = 0; j < 8; ++j) x[d0][j] *= rs * gq[d0 * 16 + 8 * h + j];
;     rope_pair8(x[0], x[1], CS + (size_t)(q >> 6) * 16 + 8 * h);
;     rope_pair8(x[2], x[3], CS + (size_t)(q & 63) * 16 + 8 * h);
.LBB0_539:
	s_and_b64 vcc, exec, s[4:5]
	s_cbranch_vccz .LBB0_543
	v_mov_b32_e32 v98, v250
	v_mov_b64_e32 v[0:1], s[92:93]
	v_readfirstlane_b32 s4, v98
	s_ashr_i32 s4, s4, 6
	v_and_b32_e32 v100, 31, v98
	s_add_i32 s5, s4, s45
	v_lshl_or_b32 v148, s5, 5, v100
	v_bfe_u32 v99, v98, 5, 1
	v_mad_i64_i32 v[0:1], s[6:7], v148, s73, v[0:1]
	s_lshl_b32 s68, s44, 1
	v_lshl_add_u64 v[0:1], v[0:1], 0, s[68:69]
	v_lshlrev_b32_e32 v172, 4, v99
	v_lshl_add_u64 v[16:17], v[0:1], 0, v[172:173]
	s_mov_b64 s[6:7], 0x2e19e00
	v_lshl_add_u64 v[18:19], v[16:17], 0, s[6:7]
	global_load_dwordx4 v[62:65], v[18:19], off offset:64
	global_load_dwordx4 v[66:69], v[18:19], off offset:96
	v_lshlrev_b32_e32 v0, 7, v148
	s_mov_b32 s6, 0x2e19000
	v_and_b32_e32 v0, 0x1f80, v0
	v_mov_b32_e32 v1, v173
	v_add_co_u32_e32 v16, vcc, s6, v16
	s_ashr_i32 s6, s5, 1
	v_lshlrev_b32_e32 v172, 6, v99
	v_lshl_add_u64 v[0:1], s[90:91], 0, v[0:1]
	s_ashr_i32 s7, s6, 31
	v_lshl_add_u64 v[12:13], v[0:1], 0, v[172:173]
	v_addc_co_u32_e32 v17, vcc, 0, v17, vcc
	s_lshl_b64 s[6:7], s[6:7], 7
	global_load_dwordx4 v[0:3], v[12:13], off offset:48
	global_load_dwordx4 v[4:7], v[12:13], off offset:32
	global_load_dwordx4 v[8:11], v[12:13], off offset:16
	s_nop 0
	global_load_dwordx4 v[12:15], v[12:13], off
	s_add_u32 s6, s90, s6
	global_load_dwordx4 v[48:51], v[16:17], off offset:3584
	global_load_dwordx4 v[52:55], v[18:19], off offset:32
	s_addc_u32 s7, s91, s7
	global_load_dwordx4 v[16:19], v172, s[6:7] offset:48
	v_readlane_b32 s8, v255, 32
	v_lshlrev_b32_e32 v110, 5, v99
	v_readlane_b32 s9, v255, 33
	s_nop 4
	global_load_dwordx4 v[24:27], v110, s[8:9] offset:144
	global_load_dwordx4 v[32:35], v110, s[8:9] offset:128
	global_load_dwordx4 v[20:23], v110, s[8:9] offset:208
	global_load_dwordx4 v[28:31], v110, s[8:9] offset:192
	global_load_dwordx4 v[70:73], v110, s[8:9] offset:16
	global_load_dwordx4 v[74:77], v110, s[8:9]
	global_load_dwordx4 v[36:39], v172, s[6:7] offset:32
	global_load_dwordx4 v[40:43], v172, s[6:7] offset:16
	global_load_dwordx4 v[44:47], v172, s[6:7]
	s_lshl_b32 s5, s43, 1
	v_readlane_b32 s6, v252, 59
	v_readlane_b32 s7, v252, 60
	s_add_u32 s6, s6, s5
	s_addc_u32 s7, s7, 0
	s_lshl_b32 s4, s4, 10
	v_lshrrev_b32_e32 v101, 5, v98
	v_lshlrev_b32_e32 v150, 3, v99
	v_ashrrev_i32_e32 v149, 31, v148
	s_mov_b64 s[12:13], 0x30ea200
	s_mov_b64 s[14:15], 0x17618180
	s_mov_b64 s[16:17], 0x31da200
	s_mov_b64 s[18:19], 0x17618200
	s_mov_b64 s[34:35], 0x32ca200
	s_mov_b64 s[44:45], 0x33ba200
	s_mov_b64 s[46:47], 0x17618300
	s_waitcnt vmcnt(0)
	v_lshlrev_b32_e32 v58, 16, v65
	v_and_b32_e32 v59, 0xffff0000, v65
	v_lshlrev_b32_e32 v56, 16, v69
	v_and_b32_e32 v57, 0xffff0000, v69
	v_lshlrev_b32_e32 v78, 16, v64
	v_and_b32_e32 v79, 0xffff0000, v64
	v_lshlrev_b32_e32 v60, 16, v68
	v_and_b32_e32 v61, 0xffff0000, v68
	v_lshlrev_b32_e32 v80, 16, v63
	v_and_b32_e32 v81, 0xffff0000, v63
	v_lshlrev_b32_e32 v82, 16, v67
	v_and_b32_e32 v83, 0xffff0000, v67
	v_lshlrev_b32_e32 v84, 16, v62
	v_and_b32_e32 v85, 0xffff0000, v62
	v_lshlrev_b32_e32 v86, 16, v66
	v_and_b32_e32 v87, 0xffff0000, v66
	global_load_dwordx4 v[62:65], v110, s[8:9] offset:80
	global_load_dwordx4 v[66:69], v110, s[8:9] offset:64
	v_mov_b32_e32 v96, v1
	v_lshlrev_b32_e32 v130, 16, v48
	v_and_b32_e32 v131, 0xffff0000, v48
	v_lshlrev_b32_e32 v122, 16, v49
	v_and_b32_e32 v123, 0xffff0000, v49
	v_pk_mul_f32 v[48:49], v[130:131], v[130:131]
	v_mov_b32_e32 v116, v17
	v_pk_mul_f32 v[124:125], v[122:123], v[122:123]
	v_add_f32_e32 v17, v48, v49
	v_lshlrev_b32_e32 v118, 16, v50
	v_and_b32_e32 v119, 0xffff0000, v50
	v_add_f32_e32 v17, v124, v17
	v_mov_b32_e32 v97, v3
	v_mov_b32_e32 v1, v2
	v_mov_b32_e32 v2, v5
	v_mov_b32_e32 v3, v7
	v_mov_b32_e32 v5, v6
	v_mov_b32_e32 v6, v9
	v_mov_b32_e32 v7, v11
	v_mov_b32_e32 v9, v10
	v_mov_b32_e32 v10, v13
	v_mov_b32_e32 v11, v15
	v_mov_b32_e32 v13, v14
	v_lshlrev_b32_e32 v14, 16, v51
	v_and_b32_e32 v15, 0xffff0000, v51
	v_pk_mul_f32 v[50:51], v[118:119], v[118:119]
	v_add_f32_e32 v17, v125, v17
	v_add_f32_e32 v17, v50, v17
	v_pk_mul_f32 v[110:111], v[14:15], v[14:15]
	v_add_f32_e32 v17, v51, v17
	v_lshlrev_b32_e32 v132, 16, v52
	v_and_b32_e32 v133, 0xffff0000, v52
	v_add_f32_e32 v17, v110, v17
	v_lshlrev_b32_e32 v126, 16, v53
	v_and_b32_e32 v127, 0xffff0000, v53
	v_pk_mul_f32 v[52:53], v[132:133], v[132:133]
	v_add_f32_e32 v17, v111, v17
	v_add_f32_e32 v17, v52, v17
	v_pk_mul_f32 v[128:129], v[126:127], v[126:127]
	v_add_f32_e32 v17, v53, v17
	v_lshlrev_b32_e32 v120, 16, v54
	v_and_b32_e32 v121, 0xffff0000, v54
	v_add_f32_e32 v17, v128, v17
	v_lshlrev_b32_e32 v112, 16, v55
	v_and_b32_e32 v113, 0xffff0000, v55
	v_pk_mul_f32 v[54:55], v[120:121], v[120:121]
	v_add_f32_e32 v17, v129, v17
	v_add_f32_e32 v17, v54, v17
	v_pk_mul_f32 v[114:115], v[112:113], v[112:113]
	v_add_f32_e32 v17, v55, v17
	v_add_f32_e32 v17, v114, v17
	v_pk_mul_f32 v[106:107], v[84:85], v[84:85]
	v_add_f32_e32 v17, v115, v17
	v_add_f32_e32 v17, v106, v17
	v_pk_mul_f32 v[102:103], v[80:81], v[80:81]
	v_add_f32_e32 v17, v107, v17
	v_add_f32_e32 v17, v102, v17
	v_pk_mul_f32 v[92:93], v[78:79], v[78:79]
	v_add_f32_e32 v17, v103, v17
	v_add_f32_e32 v17, v92, v17
	v_pk_mul_f32 v[88:89], v[58:59], v[58:59]
	v_add_f32_e32 v17, v93, v17
	v_add_f32_e32 v17, v88, v17
	v_pk_mul_f32 v[108:109], v[86:87], v[86:87]
	v_add_f32_e32 v17, v89, v17
	v_add_f32_e32 v17, v108, v17
	v_pk_mul_f32 v[104:105], v[82:83], v[82:83]
	v_add_f32_e32 v17, v109, v17
	v_add_f32_e32 v17, v104, v17
	v_pk_mul_f32 v[94:95], v[60:61], v[60:61]
	v_add_f32_e32 v17, v105, v17
	v_add_f32_e32 v17, v94, v17
	v_pk_mul_f32 v[90:91], v[56:57], v[56:57]
	v_add_f32_e32 v17, v95, v17
	v_add_f32_e32 v17, v90, v17
	v_add_f32_e32 v48, v91, v17
	ds_bpermute_b32 v49, v199, v48
	v_mov_b32_e32 v17, v18
	v_mov_b32_e32 v18, v37
	v_mov_b32_e32 v37, v38
	v_mov_b32_e32 v117, v19
	s_waitcnt lgkmcnt(0)
; #define DMA_WAIT(keep) do { if (keep) { if (TYPE == 0 && wid < 4) asm volatile("s_waitcnt vmcnt(3)" ::: "memory"); else asm volatile("s_waitcnt vmcnt(2)" ::: "memory"); } \
;     else asm volatile("s_waitcnt vmcnt(0)" ::: "memory"); } while (0)
; #define BAR() do { asm volatile("s_waitcnt lgkmcnt(0)" ::: "memory"); __builtin_amdgcn_s_barrier(); asm volatile("" ::: "memory"); } while (0)
; template <int TYPE, bool FIXREF>
; DI void attn_dense_unit(const Params& p, int layer, int head, int qb, char* lds, float bref) {
;     ...
;     const float rs = rsqrtf(ss * (1.0f / 64.0f) + 1e-6f);
;     const float* gq = p.c_q_norm + layer * 64;
; #pragma unroll
;     for (int d0 = 0; d0 < 4; ++d0)
; #pragma unroll
;       for (int j = 0; j < 8; ++j) x[d0][j] *= rs * gq[d0 * 16 + 8 * h + j];
;     rope_pair8(x[0], x[1], CS + (size_t)(q >> 6) * 16 + 8 * h);
;     rope_pair8(x[2], x[3], CS + (size_t)(q & 63) * 16 + 8 * h);
;     const float sc = 0.125f * LOG2E;
; #pragma unroll
;     for (int d0 = 0; d0 < 4; ++d0) qf[d0] = pack8(x[d0][0] * sc, x[d0][1] * sc, x[d0][2] * sc, x[d0][3] * sc, x[d0][4] * sc, x[d0][5] * sc, x[d0][6] * sc, x[d0][7] * sc);
;   }
;   typedef __attribute__((address_space(3))) unsigned lds_u32;
;   const int srow = tid >> 3, sch = (tid & 7) ^ ((srow >> 1) & 7);
;   const bf16_t* gk = Kn + (size_t)srow * ldk + sch * 8;
;   const bf16_t* gv = VT + (size_t)srow * S + sch * 8;
;   const int rrow = tid >> 2, rch = (tid & 3) ^ ((rrow >> 2) & 3);
;   const bf16_t* gr = Z + ZC_KR + (size_t)rrow * ZP + rch * 8;
;   char* wbase = lds + wid * 1024;
;     ...
;   DMA(0, R0); DMA(1, R1); DMA(2, R2); DMA_WAIT(true); BAR();
	v_add_f32_e32 v38, v48, v49
	v_fmamk_f32 v38, v38, 0x3c800000, v197
	v_mov_b32_e32 v19, v39
	v_mul_f32_e32 v39, 0x4b800000, v38
	v_cmp_gt_f32_e32 vcc, s33, v38
	s_mov_b64 s[8:9], 0x100
	s_nop 0
	v_cndmask_b32_e32 v38, v38, v39, vcc
	v_rsq_f32_e32 v48, v38
	v_mov_b32_e32 v38, v41
	v_mov_b32_e32 v41, v42
	v_mov_b32_e32 v39, v43
	v_mul_f32_e32 v42, 0x45800000, v48
	v_cndmask_b32_e32 v42, v48, v42, vcc
	s_waitcnt vmcnt(1)
	v_pk_mul_f32 v[62:63], v[62:63], v[42:43] op_sel_hi:[1,0]
	v_pk_mul_f32 v[52:53], v[70:71], v[42:43] op_sel_hi:[1,0]
	v_pk_mul_f32 v[62:63], v[62:63], v[120:121]
	v_pk_mul_f32 v[26:27], v[26:27], v[42:43] op_sel_hi:[1,0]
	v_pk_mul_f32 v[52:53], v[52:53], v[118:119]
	v_pk_mul_f32 v[54:55], v[72:73], v[42:43] op_sel_hi:[1,0]
	v_pk_mul_f32 v[26:27], v[26:27], v[58:59]
	v_pk_mul_f32 v[28:29], v[28:29], v[42:43] op_sel_hi:[1,0]
	v_pk_mul_f32 v[58:59], v[36:37], v[62:63]
	v_pk_mul_f32 v[14:15], v[54:55], v[14:15]
	s_waitcnt vmcnt(0)
	v_pk_mul_f32 v[54:55], v[66:67], v[42:43] op_sel_hi:[1,0]
	v_pk_mul_f32 v[66:67], v[68:69], v[42:43] op_sel_hi:[1,0]
	v_pk_mul_f32 v[32:33], v[32:33], v[42:43] op_sel_hi:[1,0]
	v_pk_mul_f32 v[28:29], v[28:29], v[86:87]
	v_pk_mul_f32 v[30:31], v[30:31], v[42:43] op_sel_hi:[1,0]
	v_pk_fma_f32 v[58:59], v[18:19], v[52:53], v[58:59]
	v_pk_mul_f32 v[18:19], v[18:19], v[62:63]
	v_pk_mul_f32 v[50:51], v[76:77], v[42:43] op_sel_hi:[1,0]
	v_pk_mul_f32 v[66:67], v[66:67], v[126:127]
	v_pk_mul_f32 v[64:65], v[64:65], v[42:43] op_sel_hi:[1,0]
	v_pk_mul_f32 v[32:33], v[32:33], v[84:85]
	v_pk_mul_f32 v[34:35], v[34:35], v[42:43] op_sel_hi:[1,0]
	v_pk_mul_f32 v[30:31], v[30:31], v[82:83]
	v_pk_mul_f32 v[22:23], v[22:23], v[42:43] op_sel_hi:[1,0]
	v_pk_mul_f32 v[68:69], v[28:29], v[12:13]
	v_pk_fma_f32 v[18:19], v[36:37], v[52:53], v[18:19] neg_lo:[0,0,1] neg_hi:[0,0,1]
	v_pk_mul_f32 v[50:51], v[50:51], v[122:123]
	v_pk_mul_f32 v[64:65], v[64:65], v[112:113]
	v_pk_mul_f32 v[34:35], v[34:35], v[80:81]
	v_pk_mul_f32 v[20:21], v[20:21], v[42:43] op_sel_hi:[1,0]
	v_pk_mul_f32 v[22:23], v[22:23], v[56:57]
	v_pk_mul_f32 v[56:57], v[40:41], v[66:67]
	v_pk_fma_f32 v[102:103], v[32:33], v[10:11], v[68:69]
	v_pk_mul_f32 v[68:69], v[30:31], v[8:9]
	v_pk_mul_f32 v[18:19], v[18:19], s[78:79] op_sel_hi:[1,0]
	v_pk_mul_f32 v[48:49], v[74:75], v[42:43] op_sel_hi:[1,0]
	v_pk_mul_f32 v[54:55], v[54:55], v[132:133]
	v_pk_mul_f32 v[24:25], v[24:25], v[42:43] op_sel_hi:[1,0]
	v_pk_mul_f32 v[20:21], v[20:21], v[60:61]
	v_mov_b32_e32 v42, v45
	v_mov_b32_e32 v45, v46
	v_pk_fma_f32 v[56:57], v[38:39], v[50:51], v[56:57]
	v_pk_mul_f32 v[60:61], v[16:17], v[64:65]
	v_pk_fma_f32 v[104:105], v[34:35], v[6:7], v[68:69]
	v_pk_mul_f32 v[36:37], v[116:117], v[64:65]
	v_cvt_pk_bf16_f32 v134, v18, v19
	v_pk_mul_f32 v[18:19], v[58:59], s[78:79] op_sel_hi:[1,0]
	v_pk_mul_f32 v[6:7], v[30:31], v[6:7]
	v_pk_mul_f32 v[48:49], v[48:49], v[130:131]
	v_mov_b32_e32 v43, v47
	v_pk_mul_f32 v[46:47], v[44:45], v[54:55]
	v_pk_fma_f32 v[60:61], v[116:117], v[14:15], v[60:61]
	v_pk_fma_f32 v[14:15], v[16:17], v[14:15], v[36:37] neg_lo:[0,0,1] neg_hi:[0,0,1]
	v_pk_mul_f32 v[16:17], v[56:57], s[78:79] op_sel_hi:[1,0]
	v_cvt_pk_bf16_f32 v130, v18, v19
	v_pk_mul_f32 v[10:11], v[28:29], v[10:11]
	v_pk_fma_f32 v[6:7], v[34:35], v[8:9], v[6:7] neg_lo:[0,0,1] neg_hi:[0,0,1]
	v_ashrrev_i32_e32 v18, 3, v98
	v_lshrrev_b32_e32 v28, 4, v98
	v_pk_mul_f32 v[24:25], v[24:25], v[78:79]
	v_pk_fma_f32 v[46:47], v[42:43], v[48:49], v[46:47]
	v_pk_mul_f32 v[68:69], v[20:21], v[4:5]
	v_pk_mul_f32 v[14:15], v[14:15], s[78:79] op_sel_hi:[1,0]
	v_cvt_pk_bf16_f32 v129, v16, v17
	v_pk_mul_f32 v[16:17], v[6:7], s[78:79] op_sel_hi:[1,0]
	v_xor_b32_e32 v6, v28, v98
	v_ashrrev_i32_e32 v19, 31, v18
	v_pk_fma_f32 v[106:107], v[24:25], v[2:3], v[68:69]
	v_cvt_pk_bf16_f32 v135, v14, v15
	v_pk_mul_f32 v[14:15], v[46:47], s[78:79] op_sel_hi:[1,0]
	v_pk_fma_f32 v[10:11], v[32:33], v[12:13], v[10:11] neg_lo:[0,0,1] neg_hi:[0,0,1]
	v_pk_mul_f32 v[2:3], v[20:21], v[2:3]
	v_lshlrev_b64 v[20:21], 15, v[18:19]
	v_lshlrev_b32_e32 v6, 4, v6
	v_cvt_pk_bf16_f32 v128, v14, v15
	v_pk_mul_f32 v[14:15], v[10:11], s[78:79] op_sel_hi:[1,0]
	v_pk_fma_f32 v[10:11], v[24:25], v[4:5], v[2:3] neg_lo:[0,0,1] neg_hi:[0,0,1]
	v_lshl_add_u64 v[2:3], s[6:7], 0, v[20:21]
	v_and_b32_e32 v172, 0x70, v6
	v_lshl_add_u64 v[152:153], v[2:3], 0, v[172:173]
	v_lshlrev_b32_e32 v3, 1, v98
	v_lshrrev_b32_e32 v6, 1, v98
	v_mov_b64_e32 v[4:5], s[0:1]
	v_and_b32_e32 v2, 19, v98
	v_and_b32_e32 v3, 8, v3
	v_and_b32_e32 v6, 4, v6
	v_mad_i64_i32 v[4:5], s[0:1], v18, s73, v[4:5]
	v_or3_b32 v2, v3, v2, v6
	v_lshrrev_b32_e32 v19, 1, v2
	s_add_i32 s0, s4, 0
	v_lshlrev_b32_e32 v29, 7, v2
	v_bitop3_b32 v2, v19, v99, 7 bitop3:0x6c
	v_lshl_add_u64 v[154:155], v[4:5], 0, v[172:173]
	s_mov_b32 m0, s0
	s_add_i32 s1, s0, 0x2000
	s_mov_b64 s[4:5], 0xf0000
	v_lshl_or_b32 v207, v2, 4, v29
	global_load_lds_dwordx4 v[154:155], off
	s_mov_b32 m0, s1
	v_lshl_add_u64 v[2:3], v[154:155], 0, s[4:5]
	s_add_i32 s4, s0, 0x5000
	global_load_lds_dwordx4 v[152:153], off
	s_mov_b32 m0, s4
	s_add_i32 s5, s0, 0x7000
	global_load_lds_dwordx4 v[2:3], off
	v_lshl_add_u64 v[2:3], v[152:153], 0, s[76:77]
	s_mov_b32 m0, s5
	s_mov_b64 s[6:7], 0x1e0000
	global_load_lds_dwordx4 v[2:3], off
	v_lshl_add_u64 v[2:3], v[154:155], 0, s[6:7]
	s_add_i32 s6, s0, 0xa000
	s_mov_b32 m0, s6
	s_add_i32 s7, s0, 0xc000
	global_load_lds_dwordx4 v[2:3], off
	v_lshl_add_u64 v[2:3], v[152:153], 0, s[8:9]
	s_mov_b32 m0, s7
	v_add_u32_e32 v201, 0, v207
	global_load_lds_dwordx4 v[2:3], off
	s_waitcnt vmcnt(2)
	s_waitcnt lgkmcnt(0)
	s_barrier
; #define QKR(d0, K0, K1, SOFF) do { if ((d0) < 4) { K0 = *(const bf16x8*)(lds + (SOFF) + koff[(d0) & 3]); K1 = *(const bf16x8*)(lds + (SOFF) + 32 * 128 + koff[(d0) & 3]); } \
;     else if ((d0) < NQK) { K0 = *(const bf16x8*)(lds + (SOFF) + roff[(d0) & 1]); K1 = *(const bf16x8*)(lds + (SOFF) + 32 * 64 + roff[(d0) & 1]); } } while (0)
; #define QKM(N0, N1, d0, K0, K1) do { if ((d0) == 0) { N0 = MFMA(K0, qf[0], negm); N1 = MFMA(K1, qf[0], negm); } \
;     else if ((d0) < NQK) { N0 = MFMA(K0, qf[(d0) < NQK ? (d0) : 0], N0); N1 = MFMA(K1, qf[(d0) < NQK ? (d0) : 0], N1); } } while (0)
; template <int TYPE, bool FIXREF>
; DI void attn_dense_unit(const Params& p, int layer, int head, int qb, char* lds, float bref) {
;     ...
;   float m_run = 0.f, lsum = 0.f, ls0 = 0.f, ls1 = 0.f, ls2 = 0.f; f32x16 o0, o1, negm, la;
; #pragma unroll
;   for (int i = 0; i < 16; ++i) { o0[i] = 0.f; o1[i] = 0.f; negm[i] = 0.f; la[i] = 0.f; }
;   const bf16x8 ones = {0x3F80, 0x3F80, 0x3F80, 0x3F80, 0x3F80, 0x3F80, 0x3F80, 0x3F80};
;   const int rK = (r & ~12) | ((r & 4) << 1) | ((r & 8) >> 1);
;   const int ksw = (rK >> 1) & 7, rsw = (rK >> 2) & 3, vsw = (r >> 1) & 7;
;   int koff[4], roff[2], voff[4];
; #pragma unroll
;   for (int d0 = 0; d0 < 4; ++d0) { koff[d0] = rK * 128 + (((2 * d0 + h) ^ ksw) << 4); voff[d0] = 8192 + r * 128 + (((2 * d0 + h) ^ vsw) << 4); }
; #pragma unroll
;   for (int d0 = 0; d0 < 2; ++d0) roff[d0] = 16384 + rK * 64 + (((2 * d0 + h) ^ rsw) << 4);
;     ...
;   if (FIXREF) { m_run = bref;
; #pragma unroll
;     for (int i = 0; i < 16; ++i) negm[i] = -bref; }
;   { bf16x8 ka0, ka1;
; #pragma unroll
;     for (int d0 = 0; d0 < NQK; ++d0) { QKR(d0, ka0, ka1, R0); QKM(sA0, sA1, d0, ka0, ka1); } }
	ds_read_b128 v[2:5], v201 offset:4096
	ds_read_b128 v[6:9], v201
	v_pk_mul_f32 v[42:43], v[42:43], v[54:55]
	v_pk_mul_f32 v[38:39], v[38:39], v[66:67]
	v_pk_fma_f32 v[42:43], v[44:45], v[48:49], v[42:43] neg_lo:[0,0,1] neg_hi:[0,0,1]
	v_pk_fma_f32 v[38:39], v[40:41], v[50:51], v[38:39] neg_lo:[0,0,1] neg_hi:[0,0,1]
	v_pk_mul_f32 v[42:43], v[42:43], s[78:79] op_sel_hi:[1,0]
	v_pk_mul_f32 v[38:39], v[38:39], s[78:79] op_sel_hi:[1,0]
	v_xor_b32_e32 v48, 0x80000000, v163
	v_cvt_pk_bf16_f32 v132, v42, v43
	v_cvt_pk_bf16_f32 v133, v38, v39
	v_pk_mul_f32 v[36:37], v[60:61], s[78:79] op_sel_hi:[1,0]
	v_mov_b32_e32 v49, v48
	v_mov_b32_e32 v50, v48
	v_mov_b32_e32 v51, v48
	v_mov_b32_e32 v52, v48
	v_mov_b32_e32 v53, v48
	v_mov_b32_e32 v54, v48
	v_mov_b32_e32 v55, v48
	v_mov_b32_e32 v56, v48
	v_mov_b32_e32 v57, v48
	v_mov_b32_e32 v58, v48
	v_mov_b32_e32 v59, v48
	v_mov_b32_e32 v60, v48
	v_mov_b32_e32 v61, v48
	v_mov_b32_e32 v62, v48
	v_mov_b32_e32 v63, v48
	v_pk_mul_f32 v[68:69], v[22:23], v[0:1]
	v_pk_mul_f32 v[24:25], v[10:11], s[78:79] op_sel_hi:[1,0]
	s_waitcnt lgkmcnt(0)
	v_mfma_f32_32x32x16_bf16 v[80:95], v[6:9], v[132:135], v[48:63]
	v_or_b32_e32 v6, 2, v99
	v_bitop3_b32 v6, v19, v6, 7 bitop3:0x6c
	v_lshl_or_b32 v208, v6, 4, v29
	v_fma_f32 v108, v26, v96, v68
	v_fma_f32 v109, v27, v97, v69
	v_add_u32_e32 v202, 0, v208
	ds_read_b128 v[6:9], v202 offset:4096
	ds_read_b128 v[10:13], v202
	v_cvt_pk_bf16_f32 v131, v36, v37
	v_mfma_f32_32x32x16_bf16 v[64:79], v[2:5], v[132:135], v[48:63]
	v_mul_f32_e64 v2, v22, v96
	v_mul_f32_e64 v3, v23, v97
	v_mul_f32_e64 v4, v102, s78
	v_mul_f32_e64 v5, v103, s78
	v_fma_f32 v0, v26, v0, -v2
	v_fma_f32 v1, v27, v1, -v3
	v_cvt_pk_bf16_f32 v140, v14, v15
	v_pk_mul_f32 v[0:1], v[0:1], s[78:79] op_sel_hi:[1,0]
	v_cvt_pk_bf16_f32 v141, v16, v17
	v_cvt_pk_bf16_f32 v143, v0, v1
	v_or_b32_e32 v0, 4, v99
	s_waitcnt lgkmcnt(0)
	v_mfma_f32_32x32x16_bf16 v[80:95], v[10:13], v[128:131], v[80:95]
	v_bitop3_b32 v0, v19, v0, 7 bitop3:0x6c
	v_lshl_or_b32 v209, v0, 4, v29
	v_add_u32_e32 v204, 0, v209
	ds_read_b128 v[0:3], v204 offset:4096
	ds_read_b128 v[10:13], v204
	v_cvt_pk_bf16_f32 v142, v24, v25
	v_cvt_pk_bf16_f32 v136, v4, v5
	v_or_b32_e32 v4, 6, v99
	v_mfma_f32_32x32x16_bf16 v[64:79], v[6:9], v[128:131], v[64:79]
	v_bitop3_b32 v4, v19, v4, 7 bitop3:0x6c
	v_lshl_or_b32 v210, v4, 4, v29
	v_mul_f32_e64 v6, v104, s78
	v_mul_f32_e64 v7, v105, s78
	v_mul_f32_e64 v8, v106, s78
	v_mul_f32_e64 v9, v107, s78
	v_add_u32_e32 v203, 0, v210
	v_cvt_pk_bf16_f32 v137, v6, v7
	v_cvt_pk_bf16_f32 v138, v8, v9
	s_waitcnt lgkmcnt(0)
	v_mfma_f32_32x32x16_bf16 v[80:95], v[10:13], v[140:143], v[80:95]
	ds_read_b128 v[4:7], v203 offset:4096
	ds_read_b128 v[8:11], v203
	v_mul_f32_e64 v14, v108, s78
	v_mul_f32_e64 v15, v109, s78
	s_add_i32 s8, s0, 0x11000
	v_cvt_pk_bf16_f32 v139, v14, v15
	v_bfe_u32 v12, v98, 1, 3
	s_add_u32 s10, s92, s42
	s_addc_u32 s11, s93, 0
	v_mfma_f32_32x32x16_bf16 v[64:79], v[0:3], v[140:143], v[64:79]
	v_lshlrev_b32_e32 v0, 7, v100
	v_bitop3_b32 v2, v101, v12, 1 bitop3:0x6c
	v_bitop3_b32 v3, v99, v12, 2 bitop3:0x36
	v_or_b32_e32 v1, 0x2000, v0
	v_lshlrev_b32_e32 v2, 4, v2
	v_lshlrev_b32_e32 v3, 4, v3
	v_lshl_add_u64 v[158:159], s[10:11], 0, v[20:21]
	s_waitcnt lgkmcnt(0)
	v_mfma_f32_32x32x16_bf16 v[80:95], v[8:11], v[136:139], v[80:95]
	v_bitop3_b32 v8, v99, v12, 4 bitop3:0x36
	v_bitop3_b32 v9, v99, v12, 6 bitop3:0x36
	v_lshlrev_b32_e32 v8, 4, v8
	v_lshlrev_b32_e32 v9, 4, v9
	s_add_u32 s10, s92, s31
	v_or_b32_e32 v211, v2, v1
	v_or_b32_e32 v212, v3, v1
	v_mfma_f32_32x32x16_bf16 v[64:79], v[4:7], v[136:139], v[64:79]
	v_or_b32_e32 v2, v2, v0
	v_or_b32_e32 v3, v3, v0
	v_or_b32_e32 v4, v8, v0
	v_or_b32_e32 v5, v9, v0
	v_bitop3_b32 v0, v28, 7, v98 bitop3:0x48
	s_addc_u32 s11, s93, 0
	v_or_b32_e32 v213, v8, v1
	v_or_b32_e32 v214, v9, v1
	v_lshlrev_b32_e32 v172, 4, v0
	v_mov_b64_e32 v[0:1], s[10:11]
	v_mov_b32_e32 v32, 0
	v_mad_i64_i32 v[160:161], s[10:11], v18, s73, v[0:1]
	s_mov_b32 s9, -4
	v_add_u32_e32 v206, 0, v2
	v_add_u32_e32 v205, 0, v3
	v_add_u32_e32 v200, 0, v4
	v_add_u32_e32 v151, 0, v5
	v_mov_b32_e32 v33, v32
	v_mov_b32_e32 v34, v32
	v_mov_b32_e32 v35, v32
	v_mov_b32_e32 v36, v32
	v_mov_b32_e32 v37, v32
	v_mov_b32_e32 v38, v32
	v_mov_b32_e32 v39, v32
	v_mov_b32_e32 v40, v32
	v_mov_b32_e32 v41, v32
	v_mov_b32_e32 v42, v32
	v_mov_b32_e32 v43, v32
	v_mov_b32_e32 v44, v32
	v_mov_b32_e32 v45, v32
	v_mov_b32_e32 v46, v32
	v_mov_b32_e32 v47, v32
	v_mov_b32_e32 v16, v32
	v_mov_b32_e32 v17, v32
	v_mov_b32_e32 v18, v32
	v_mov_b32_e32 v19, v32
	v_mov_b32_e32 v20, v32
	v_mov_b32_e32 v21, v32
	v_mov_b32_e32 v22, v32
	v_mov_b32_e32 v23, v32
	v_mov_b32_e32 v24, v32
	v_mov_b32_e32 v25, v32
	v_mov_b32_e32 v26, v32
	v_mov_b32_e32 v27, v32
	v_mov_b32_e32 v28, v32
	v_mov_b32_e32 v29, v32
	v_mov_b32_e32 v30, v32
	v_mov_b32_e32 v31, v32
	v_mov_b32_e32 v0, v32
	v_mov_b32_e32 v1, v32
	v_mov_b32_e32 v2, v32
	v_mov_b32_e32 v3, v32
	v_mov_b32_e32 v4, v32
	v_mov_b32_e32 v5, v32
	v_mov_b32_e32 v6, v32
	v_mov_b32_e32 v7, v32
	v_mov_b32_e32 v8, v32
	v_mov_b32_e32 v9, v32
	v_mov_b32_e32 v10, v32
	v_mov_b32_e32 v11, v32
	v_mov_b32_e32 v12, v32
	v_mov_b32_e32 v13, v32
	v_mov_b32_e32 v14, v32
	v_mov_b32_e32 v15, v32
	v_mov_b32_e32 v156, v32
	v_mov_b32_e32 v157, v32
	v_mov_b32_e32 v162, v32
	v_mov_b32_e32 v163, v32
	s_mov_b64 s[42:43], 0x17618280
	.p2align	6

; template <int TYPE, bool FIXREF>
; DI void attn_dense_unit(const Params& p, int layer, int head, int qb, char* lds, float bref) {
;     ...
;   if (TYPE == 0) {
;     const bf16_t* qp = (const bf16_t*)(p.ws + OFF_QA) + (size_t)q * 768 + head * 96 + 8 * h;
;     float x[6][8];
; #pragma unroll
;     for (int d0 = 0; d0 < 6; ++d0) unpack8(*(const u32x4*)(qp + d0 * 16), x[d0]);
;     rope_pair8(x[4], x[5], CS + (size_t)q * 16 + 8 * h);
;     const float sc = 0.10206207261596577f * LOG2E;
; #pragma unroll
;     for (int d0 = 0; d0 < 6; ++d0) qf[d0] = pack8(x[d0][0] * sc, x[d0][1] * sc, x[d0][2] * sc, x[d0][3] * sc, x[d0][4] * sc, x[d0][5] * sc, x[d0][6] * sc, x[d0][7] * sc);
;     ...
;   const int rK = (r & ~12) | ((r & 4) << 1) | ((r & 8) >> 1);
;   const int ksw = (rK >> 1) & 7, rsw = (rK >> 2) & 3, vsw = (r >> 1) & 7;
;   int koff[4], roff[2], voff[4];
; #pragma unroll
;   for (int d0 = 0; d0 < 4; ++d0) { koff[d0] = rK * 128 + (((2 * d0 + h) ^ ksw) << 4); voff[d0] = 8192 + r * 128 + (((2 * d0 + h) ^ vsw) << 4); }
; #pragma unroll
;   for (int d0 = 0; d0 < 2; ++d0) roff[d0] = 16384 + rK * 64 + (((2 * d0 + h) ^ rsw) << 4);
.LBB0_553:
	v_mad_i64_i32 v[54:55], s[4:5], v43, s73, 0
	s_waitcnt vmcnt(0)
	v_lshlrev_b32_e32 v44, 16, v36
	v_and_b32_e32 v45, 0xffff0000, v36
	s_mov_b32 s4, 0x3e16c740
	v_lshlrev_b32_e32 v36, 16, v37
	v_and_b32_e32 v37, 0xffff0000, v37
	v_lshlrev_b32_e32 v46, 16, v38
	v_and_b32_e32 v47, 0xffff0000, v38
	v_lshlrev_b32_e32 v38, 16, v39
	v_and_b32_e32 v39, 0xffff0000, v39
	v_pk_mul_f32 v[36:37], v[36:37], s[4:5] op_sel_hi:[1,0]
	v_pk_mul_f32 v[38:39], v[38:39], s[4:5] op_sel_hi:[1,0]
	v_cvt_pk_bf16_f32 v133, v36, v37
	v_cvt_pk_bf16_f32 v135, v38, v39
	v_lshlrev_b32_e32 v36, 16, v32
	v_and_b32_e32 v37, 0xffff0000, v32
	v_lshlrev_b32_e32 v32, 16, v33
	v_and_b32_e32 v33, 0xffff0000, v33
	v_lshlrev_b32_e32 v38, 16, v34
	v_and_b32_e32 v39, 0xffff0000, v34
	v_lshlrev_b32_e32 v34, 16, v35
	v_and_b32_e32 v35, 0xffff0000, v35
	v_pk_mul_f32 v[32:33], v[32:33], s[4:5] op_sel_hi:[1,0]
	v_pk_mul_f32 v[34:35], v[34:35], s[4:5] op_sel_hi:[1,0]
	v_cvt_pk_bf16_f32 v129, v32, v33
	v_cvt_pk_bf16_f32 v131, v34, v35
	v_lshlrev_b32_e32 v32, 16, v28
	v_and_b32_e32 v33, 0xffff0000, v28
	v_lshlrev_b32_e32 v28, 16, v29
	v_and_b32_e32 v29, 0xffff0000, v29
	v_lshlrev_b32_e32 v34, 16, v30
	v_and_b32_e32 v35, 0xffff0000, v30
	v_lshlrev_b32_e32 v30, 16, v31
	v_and_b32_e32 v31, 0xffff0000, v31
	v_pk_mul_f32 v[28:29], v[28:29], s[4:5] op_sel_hi:[1,0]
	v_pk_mul_f32 v[30:31], v[30:31], s[4:5] op_sel_hi:[1,0]
	v_cvt_pk_bf16_f32 v145, v28, v29
	v_cvt_pk_bf16_f32 v147, v30, v31
	v_lshlrev_b32_e32 v28, 16, v24
	v_and_b32_e32 v29, 0xffff0000, v24
	v_lshlrev_b32_e32 v30, 16, v26
	v_and_b32_e32 v31, 0xffff0000, v26
	v_lshlrev_b32_e32 v26, 16, v27
	v_and_b32_e32 v27, 0xffff0000, v27
	v_pk_mul_f32 v[28:29], v[28:29], s[4:5] op_sel_hi:[1,0]
	v_lshlrev_b32_e32 v24, 16, v25
	v_and_b32_e32 v25, 0xffff0000, v25
	v_pk_mul_f32 v[26:27], v[26:27], s[4:5] op_sel_hi:[1,0]
	v_pk_mul_f32 v[24:25], v[24:25], s[4:5] op_sel_hi:[1,0]
	v_cvt_pk_bf16_f32 v140, v28, v29
	v_cvt_pk_bf16_f32 v143, v26, v27
	v_lshlrev_b32_e32 v26, 16, v0
	v_and_b32_e32 v27, 0xffff0000, v0
	v_mov_b32_e32 v28, v21
	v_mov_b32_e32 v29, v23
	v_mov_b32_e32 v21, v22
	v_cvt_pk_bf16_f32 v141, v24, v25
	v_lshlrev_b32_e32 v24, 16, v4
	v_and_b32_e32 v25, 0xffff0000, v4
	v_pk_mul_f32 v[22:23], v[20:21], v[26:27]
	v_pk_mul_f32 v[26:27], v[28:29], v[26:27]
	v_pk_fma_f32 v[22:23], v[28:29], v[24:25], v[22:23]
	v_pk_fma_f32 v[20:21], v[20:21], v[24:25], v[26:27] neg_lo:[0,0,1] neg_hi:[0,0,1]
	v_lshlrev_b32_e32 v0, 16, v1
	v_pk_mul_f32 v[20:21], v[20:21], s[4:5] op_sel_hi:[1,0]
	v_and_b32_e32 v1, 0xffff0000, v1
	v_cvt_pk_bf16_f32 v148, v20, v21
	v_pk_mul_f32 v[20:21], v[22:23], s[4:5] op_sel_hi:[1,0]
	v_mov_b32_e32 v22, v17
	v_mov_b32_e32 v23, v19
	v_mov_b32_e32 v17, v18
	v_lshlrev_b32_e32 v4, 16, v5
	v_and_b32_e32 v5, 0xffff0000, v5
	v_pk_mul_f32 v[18:19], v[16:17], v[0:1]
	v_pk_mul_f32 v[0:1], v[22:23], v[0:1]
	v_pk_fma_f32 v[18:19], v[22:23], v[4:5], v[18:19]
	v_pk_fma_f32 v[0:1], v[16:17], v[4:5], v[0:1] neg_lo:[0,0,1] neg_hi:[0,0,1]
	v_lshlrev_b32_e32 v16, 16, v2
	v_pk_mul_f32 v[0:1], v[0:1], s[4:5] op_sel_hi:[1,0]
	v_and_b32_e32 v17, 0xffff0000, v2
	v_cvt_pk_bf16_f32 v149, v0, v1
	v_pk_mul_f32 v[0:1], v[18:19], s[4:5] op_sel_hi:[1,0]
	v_mov_b32_e32 v18, v13
	v_mov_b32_e32 v19, v15
	v_mov_b32_e32 v13, v14
	v_lshlrev_b32_e32 v4, 16, v6
	v_and_b32_e32 v5, 0xffff0000, v6
	v_pk_mul_f32 v[14:15], v[12:13], v[16:17]
	v_pk_mul_f32 v[16:17], v[18:19], v[16:17]
	v_pk_fma_f32 v[14:15], v[18:19], v[4:5], v[14:15]
	v_pk_fma_f32 v[4:5], v[12:13], v[4:5], v[16:17] neg_lo:[0,0,1] neg_hi:[0,0,1]
	v_lshlrev_b32_e32 v2, 16, v3
	v_and_b32_e32 v3, 0xffff0000, v3
	v_mov_b32_e32 v12, v9
	v_mov_b32_e32 v13, v11
	v_mov_b32_e32 v9, v10
	v_lshlrev_b32_e32 v6, 16, v7
	v_and_b32_e32 v7, 0xffff0000, v7
	v_pk_mul_f32 v[10:11], v[8:9], v[2:3]
	v_pk_mul_f32 v[2:3], v[12:13], v[2:3]
	v_pk_fma_f32 v[10:11], v[12:13], v[6:7], v[10:11]
	v_pk_fma_f32 v[2:3], v[8:9], v[6:7], v[2:3] neg_lo:[0,0,1] neg_hi:[0,0,1]
	v_cvt_pk_bf16_f32 v137, v0, v1
	v_pk_mul_f32 v[2:3], v[2:3], s[4:5] op_sel_hi:[1,0]
	v_lshlrev_b32_e32 v1, 1, v42
	v_cvt_pk_bf16_f32 v151, v2, v3
	v_pk_mul_f32 v[2:3], v[10:11], s[4:5] op_sel_hi:[1,0]
	v_and_b32_e32 v0, 19, v42
	v_cvt_pk_bf16_f32 v139, v2, v3
	v_lshrrev_b32_e32 v2, 1, v42
	v_and_b32_e32 v1, 8, v1
	v_and_b32_e32 v3, 4, v2
	v_pk_mul_f32 v[4:5], v[4:5], s[4:5] op_sel_hi:[1,0]
	v_or3_b32 v0, v1, v0, v3
	v_cvt_pk_bf16_f32 v150, v4, v5
	v_pk_mul_f32 v[4:5], v[14:15], s[4:5] op_sel_hi:[1,0]
	v_lshrrev_b32_e32 v1, 1, v0
	v_bitop3_b32 v2, v40, v2, 7 bitop3:0x78
	v_cvt_pk_bf16_f32 v138, v4, v5
	v_lshlrev_b32_e32 v5, 7, v0
	v_bitop3_b32 v7, v1, v40, 7 bitop3:0x6c
	v_lshlrev_b32_e32 v58, 4, v2
	v_or_b32_e32 v2, 2, v40
	v_bfe_u32 v4, v42, 1, 3
	v_lshl_or_b32 v212, v7, 4, v5
	v_bitop3_b32 v7, v1, v2, 7 bitop3:0x6c
	v_lshl_or_b32 v214, v7, 4, v5
	v_bitop3_b32 v7, v40, v4, 2 bitop3:0x36
	v_lshlrev_b32_e32 v60, 4, v7
	v_or_b32_e32 v7, 4, v40
	s_waitcnt lgkmcnt(0)
	s_barrier
; #define QKR(d0, K0, K1, SOFF) do { if ((d0) < 4) { K0 = *(const bf16x8*)(lds + (SOFF) + koff[(d0) & 3]); K1 = *(const bf16x8*)(lds + (SOFF) + 32 * 128 + koff[(d0) & 3]); } \
;     else if ((d0) < NQK) { K0 = *(const bf16x8*)(lds + (SOFF) + roff[(d0) & 1]); K1 = *(const bf16x8*)(lds + (SOFF) + 32 * 64 + roff[(d0) & 1]); } } while (0)
; #define QKM(N0, N1, d0, K0, K1) do { if ((d0) == 0) { N0 = MFMA(K0, qf[0], negm); N1 = MFMA(K1, qf[0], negm); } \
;     else if ((d0) < NQK) { N0 = MFMA(K0, qf[(d0) < NQK ? (d0) : 0], N0); N1 = MFMA(K1, qf[(d0) < NQK ? (d0) : 0], N1); } } while (0)
; template <int TYPE, bool FIXREF>
; DI void attn_dense_unit(const Params& p, int layer, int head, int qb, char* lds, float bref) {
;     ...
;   float m_run = 0.f, lsum = 0.f, ls0 = 0.f, ls1 = 0.f, ls2 = 0.f; f32x16 o0, o1, negm, la;
; #pragma unroll
;   for (int i = 0; i < 16; ++i) { o0[i] = 0.f; o1[i] = 0.f; negm[i] = 0.f; la[i] = 0.f; }
;     ...
;   { bf16x8 ka0, ka1;
; #pragma unroll
;     for (int d0 = 0; d0 < NQK; ++d0) { QKR(d0, ka0, ka1, R0); QKM(sA0, sA1, d0, ka0, ka1); } }
	v_add_u32_e32 v199, 0, v212
	v_cvt_pk_bf16_f32 v136, v20, v21
	v_bitop3_b32 v7, v1, v7, 7 bitop3:0x6c
	ds_read_b128 v[16:19], v199 offset:4096
	ds_read_b128 v[20:23], v199
	v_lshl_or_b32 v216, v7, 4, v5
	v_bitop3_b32 v7, v40, v4, 4 bitop3:0x36
	v_lshlrev_b32_e32 v61, 4, v7
	v_or_b32_e32 v7, 6, v40
	v_pk_mul_f32 v[44:45], v[44:45], s[4:5] op_sel_hi:[1,0]
	v_pk_mul_f32 v[46:47], v[46:47], s[4:5] op_sel_hi:[1,0]
	v_bitop3_b32 v1, v1, v7, 7 bitop3:0x6c
	v_cvt_pk_bf16_f32 v132, v44, v45
	v_cvt_pk_bf16_f32 v134, v46, v47
	v_pk_mul_f32 v[36:37], v[36:37], s[4:5] op_sel_hi:[1,0]
	v_pk_mul_f32 v[38:39], v[38:39], s[4:5] op_sel_hi:[1,0]
	v_pk_mul_f32 v[32:33], v[32:33], s[4:5] op_sel_hi:[1,0]
	v_pk_mul_f32 v[34:35], v[34:35], s[4:5] op_sel_hi:[1,0]
	v_lshrrev_b32_e32 v3, 2, v0
	v_lshl_or_b32 v218, v1, 4, v5
	v_bitop3_b32 v1, v40, v4, 6 bitop3:0x36
	v_lshlrev_b32_e32 v248, 3, v40
	v_cvt_pk_bf16_f32 v128, v36, v37
	v_cvt_pk_bf16_f32 v130, v38, v39
	v_cvt_pk_bf16_f32 v144, v32, v33
	v_cvt_pk_bf16_f32 v146, v34, v35
	v_pk_mul_f32 v[30:31], v[30:31], s[4:5] op_sel_hi:[1,0]
	v_lshlrev_b32_e32 v56, 7, v41
	v_lshlrev_b32_e32 v62, 4, v1
	v_bitop3_b32 v1, v3, v40, 3 bitop3:0x6c
	s_waitcnt lgkmcnt(0)
	v_mfma_f32_32x32x16_bf16 v[32:47], v[20:23], v[132:135], 0
	v_cvt_pk_bf16_f32 v142, v30, v31
	v_add_u32_e32 v200, 0, v214
	ds_read_b128 v[64:67], v200 offset:4096
	ds_read_b128 v[68:71], v200
	v_add_u32_e32 v201, 0, v216
	v_add_u32_e32 v202, 0, v218
	v_lshlrev_b32_e32 v48, 6, v0
	v_lshlrev_b32_e32 v72, 4, v1
	v_mfma_f32_32x32x16_bf16 v[16:31], v[16:19], v[132:135], 0
	v_bitop3_b32 v1, v3, v2, 3 bitop3:0x6c
	v_lshlrev_b32_e32 v63, 4, v1
	v_or_b32_e32 v0, 0x4000, v48
	v_or_b32_e32 v59, v63, v0
	s_lshl_b32 s68, s30, 21
	v_or_b32_e32 v6, 0x2000, v56
	s_mov_b32 s4, s69
	s_waitcnt lgkmcnt(0)
	v_mfma_f32_32x32x16_bf16 v[32:47], v[68:71], v[128:131], v[32:47]
	s_mov_b32 s5, s69
	v_or_b32_e32 v213, v58, v6
	v_or_b32_e32 v215, v60, v6
	v_or_b32_e32 v217, v61, v6
	v_or_b32_e32 v219, v62, v6
	v_or_b32_e32 v57, v72, v0
	s_lshl_b32 s30, s30, 7
	v_mfma_f32_32x32x16_bf16 v[16:31], v[64:67], v[128:131], v[16:31]
	ds_read_b128 v[64:67], v201 offset:4096
	ds_read_b128 v[68:71], v201
	s_mov_b32 s31, s69
	s_mov_b32 s6, s69
	s_mov_b32 s7, s69
	s_mov_b32 s8, s69
	s_mov_b32 s9, s69
	s_mov_b32 s10, s69
	s_waitcnt lgkmcnt(0)
	v_mfma_f32_32x32x16_bf16 v[32:47], v[68:71], v[144:147], v[32:47]
	s_mov_b32 s11, s69
	s_mov_b32 s12, s69
	s_mov_b32 s13, s69
	s_mov_b32 s14, s69
	s_mov_b32 s15, s69
	s_mov_b32 s16, s69
	s_mov_b32 s17, s69
	v_mfma_f32_32x32x16_bf16 v[16:31], v[64:67], v[144:147], v[16:31]
	ds_read_b128 v[64:67], v202 offset:4096
	ds_read_b128 v[68:71], v202
	s_mov_b32 s18, s69
	s_mov_b32 s19, s69
	v_mov_b64_e32 v[0:1], s[4:5]
	v_mov_b64_e32 v[14:15], s[18:19]
	v_mov_b64_e32 v[2:3], s[6:7]
	v_mov_b64_e32 v[4:5], s[8:9]
	s_waitcnt lgkmcnt(0)
	v_mfma_f32_32x32x16_bf16 v[32:47], v[68:71], v[140:143], v[32:47]
	v_mov_b64_e32 v[6:7], s[10:11]
	v_mov_b64_e32 v[8:9], s[12:13]
	v_mov_b64_e32 v[10:11], s[14:15]
	v_mov_b64_e32 v[12:13], s[16:17]
	s_add_i32 s7, s43, 0x11000
	s_add_i32 s6, s43, 0x13000
	s_mov_b32 s8, -4
	v_mfma_f32_32x32x16_bf16 v[16:31], v[64:67], v[140:143], v[16:31]
	v_or_b32_e32 v64, v72, v48
	v_add_u32_e32 v210, 0, v64
	ds_read_b128 v[64:67], v210 offset:18432
	ds_read_b128 v[68:71], v210 offset:16384
	v_or_b32_e32 v48, v63, v48
	v_add_u32_e32 v211, 0, v48
	v_add_u32_e32 v208, 0, v57
	v_add_u32_e32 v207, 0, v59
	s_waitcnt lgkmcnt(0)
; #define QKR(d0, K0, K1, SOFF) do { if ((d0) < 4) { K0 = *(const bf16x8*)(lds + (SOFF) + koff[(d0) & 3]); K1 = *(const bf16x8*)(lds + (SOFF) + 32 * 128 + koff[(d0) & 3]); } \
;     else if ((d0) < NQK) { K0 = *(const bf16x8*)(lds + (SOFF) + roff[(d0) & 1]); K1 = *(const bf16x8*)(lds + (SOFF) + 32 * 64 + roff[(d0) & 1]); } } while (0)
; #define QKM(N0, N1, d0, K0, K1) do { if ((d0) == 0) { N0 = MFMA(K0, qf[0], negm); N1 = MFMA(K1, qf[0], negm); } \
;     else if ((d0) < NQK) { N0 = MFMA(K0, qf[(d0) < NQK ? (d0) : 0], N0); N1 = MFMA(K1, qf[(d0) < NQK ? (d0) : 0], N1); } } while (0)
; template <int TYPE, bool FIXREF>
; DI void attn_dense_unit(const Params& p, int layer, int head, int qb, char* lds, float bref) {
;     ...
;   { bf16x8 ka0, ka1;
; #pragma unroll
;     for (int d0 = 0; d0 < NQK; ++d0) { QKR(d0, ka0, ka1, R0); QKM(sA0, sA1, d0, ka0, ka1); } }
;   if (!FIXREF) { float mx0; ROWMAX(sA0, sA1, mx0); m_run = mx0;
; #pragma unroll
;     for (int i = 0; i < 16; ++i) { sA0[i] -= mx0; sA1[i] -= mx0; negm[i] = -mx0; } }
	v_mfma_f32_32x32x16_bf16 v[32:47], v[68:71], v[148:151], v[32:47]
	v_mfma_f32_32x32x16_bf16 v[16:31], v[64:67], v[148:151], v[16:31]
	ds_read_b128 v[64:67], v211 offset:18432
	ds_read_b128 v[68:71], v211 offset:16384
	s_waitcnt lgkmcnt(0)
	v_mfma_f32_32x32x16_bf16 v[32:47], v[68:71], v[136:139], v[32:47]
	v_mfma_f32_32x32x16_bf16 v[16:31], v[64:67], v[136:139], v[16:31]
	s_nop 10
	v_max_f32_e32 v48, v33, v33
	v_max_f32_e32 v63, v32, v32
	v_max_f32_e32 v48, v63, v48
	v_and_b32_e32 v64, 64, v196
	v_add_u32_e32 v64, 64, v64
	v_max3_f32 v63, v34, v35, v17
	v_max3_f32 v48, v48, v16, v18
	v_max3_f32 v48, v48, v19, v36
	v_max3_f32 v63, v63, v38, v39
	v_max3_f32 v48, v48, v37, v20
	v_max3_f32 v63, v63, v22, v23
	v_max3_f32 v48, v48, v21, v40
	v_max3_f32 v63, v63, v42, v43
	v_max3_f32 v48, v48, v41, v24
	v_max3_f32 v63, v63, v26, v27
	v_max3_f32 v48, v48, v25, v44
	v_max3_f32 v63, v63, v46, v47
	v_max3_f32 v48, v48, v45, v28
	v_max3_f32 v63, v63, v30, v31
	v_max3_f32 v48, v48, v29, v63
	v_xor_b32_e32 v63, 32, v196
	v_cmp_lt_i32_e32 vcc, v63, v64
	s_nop 1
	v_cndmask_b32_e32 v63, v196, v63, vcc
	v_lshlrev_b32_e32 v249, 2, v63
	ds_bpermute_b32 v63, v249, v48
	s_waitcnt lgkmcnt(0)
	v_max_f32_e32 v63, v63, v63
	v_max_f32_e32 v209, v48, v63
	v_sub_f32_e32 v70, v22, v209
	v_and_b32_e32 v22, 7, v49
	v_sub_f32_e32 v65, v17, v209
	v_sub_f32_e32 v64, v16, v209
	v_lshl_add_u64 v[16:17], s[68:69], 0, v[52:53]
	v_lshlrev_b32_e32 v172, 4, v22
	v_lshl_add_u64 v[160:161], v[16:17], 0, v[172:173]
	v_and_b32_e32 v16, 3, v49
	v_lshlrev_b32_e32 v16, 4, v16
	v_mov_b32_e32 v17, v173
	v_sub_f32_e32 v69, v21, v209
	v_sub_f32_e32 v68, v20, v209
	v_sub_f32_e32 v67, v19, v209
	v_sub_f32_e32 v66, v18, v209
	v_or_b32_e32 v18, v58, v56
	v_or_b32_e32 v19, v60, v56
	v_or_b32_e32 v20, v61, v56
	v_or_b32_e32 v21, v62, v56
	v_lshl_add_u64 v[162:163], v[54:55], 0, v[16:17]
	v_lshl_add_u64 v[16:17], v[50:51], 0, s[30:31]
	v_xor_b32_e32 v48, 0x80000000, v209
	v_sub_f32_e32 v79, v31, v209
	v_sub_f32_e32 v78, v30, v209
	v_sub_f32_e32 v77, v29, v209
	v_sub_f32_e32 v76, v28, v209
	v_sub_f32_e32 v75, v27, v209
	v_sub_f32_e32 v74, v26, v209
	v_sub_f32_e32 v73, v25, v209
	v_sub_f32_e32 v72, v24, v209
	v_sub_f32_e32 v71, v23, v209
	v_lshl_add_u64 v[164:165], v[16:17], 0, v[172:173]
	v_mov_b32_e32 v172, v173
	v_add_u32_e32 v206, 0, v18
	v_add_u32_e32 v205, 0, v19
	v_add_u32_e32 v204, 0, v20
	v_add_u32_e32 v203, 0, v21
	v_mov_b64_e32 v[30:31], v[14:15]
	v_sub_f32_e32 v95, v47, v209
	v_sub_f32_e32 v94, v46, v209
	v_sub_f32_e32 v93, v45, v209
	v_sub_f32_e32 v92, v44, v209
	v_sub_f32_e32 v91, v43, v209
	v_sub_f32_e32 v90, v42, v209
	v_sub_f32_e32 v89, v41, v209
	v_sub_f32_e32 v88, v40, v209
	v_sub_f32_e32 v87, v39, v209
	v_sub_f32_e32 v86, v38, v209
	v_sub_f32_e32 v85, v37, v209
	v_sub_f32_e32 v84, v36, v209
	v_sub_f32_e32 v83, v35, v209
	v_sub_f32_e32 v82, v34, v209
	v_sub_f32_e32 v81, v33, v209
	v_sub_f32_e32 v80, v32, v209
	v_mov_b64_e32 v[28:29], v[12:13]
	v_mov_b64_e32 v[26:27], v[10:11]
	v_mov_b64_e32 v[24:25], v[8:9]
	v_mov_b64_e32 v[22:23], v[6:7]
	v_mov_b64_e32 v[20:21], v[4:5]
	v_mov_b64_e32 v[18:19], v[2:3]
	v_mov_b64_e32 v[16:17], v[0:1]
	v_mov_b64_e32 v[184:185], v[172:173]
	v_mov_b64_e32 v[186:187], v[172:173]
	v_mov_b32_e32 v49, v48
	v_mov_b32_e32 v50, v48
	v_mov_b32_e32 v51, v48
	v_mov_b32_e32 v52, v48
	v_mov_b32_e32 v53, v48
	v_mov_b32_e32 v54, v48
	v_mov_b32_e32 v55, v48
	v_mov_b32_e32 v56, v48
	v_mov_b32_e32 v57, v48
	v_mov_b32_e32 v58, v48
	v_mov_b32_e32 v59, v48
	v_mov_b32_e32 v60, v48
	v_mov_b32_e32 v61, v48
	v_mov_b32_e32 v62, v48
	v_mov_b32_e32 v63, v48
	s_branch .LBB0_555
	.p2align	6
